# hgrn chain completion: skip the L2 write-back (buffer_wbl2) when the census says every group sits on one XCC (same condition as the light barriers)
# speedup vs baseline: 1.0085x; 1.0045x over previous
.LBB0_689:
	ds_write_b32 v87, v77 offset:35840
	s_waitcnt lgkmcnt(0)
	s_barrier
	ds_read2st64_b32 v[78:79], v91 offset0:140 offset1:142
	ds_read2st64_b32 v[84:85], v91 offset0:144 offset1:146
	v_exp_f32_e32 v82, v82
	v_exp_f32_e32 v83, v83
	v_exp_f32_e32 v98, v75
	v_exp_f32_e32 v99, v76
	v_exp_f32_e32 v102, v73
	v_exp_f32_e32 v103, v74
	s_waitcnt lgkmcnt(1)
	v_add_f32_e32 v106, 0, v78
	v_cndmask_b32_e64 v91, 0, v79, s[8:9]
	v_exp_f32_e32 v75, v72
	v_pk_add_f32 v[72:73], v[82:83], 1.0 op_sel_hi:[1,0] neg_lo:[1,0] neg_hi:[1,0]
	v_pk_add_f32 v[82:83], v[98:99], 1.0 op_sel_hi:[1,0] neg_lo:[1,0] neg_hi:[1,0]
	v_pk_add_f32 v[98:99], v[102:103], 1.0 op_sel_hi:[1,0] neg_lo:[1,0] neg_hi:[1,0]
	v_exp_f32_e32 v102, v69
	v_cndmask_b32_e64 v69, 0, v106, s[6:7]
	s_waitcnt lgkmcnt(0)
	v_cndmask_b32_e64 v77, 0, v84, s[12:13]
	v_add_f32_e32 v107, v69, v91
	v_mov_b32_e32 v76, v79
	v_exp_f32_e32 v86, v96
	v_exp_f32_e32 v87, v97
	v_cndmask_b32_e64 v97, 0, v85, s[10:11]
	v_pk_add_f32 v[76:77], v[106:107], v[76:77]
	v_mov_b32_e32 v96, v84
	v_pk_add_f32 v[76:77], v[76:77], v[96:97]
	v_exp_f32_e32 v103, v57
	v_add_f32_e32 v69, v48, v77
	v_mov_b32_e32 v48, v85
	v_pk_add_f32 v[48:49], v[76:77], v[48:49]
	v_add_f32_e32 v68, v68, v77
	v_sub_f32_e32 v69, v48, v69
	v_exp_f32_e32 v78, v69
	v_add_f32_e32 v69, v70, v77
	v_sub_f32_e32 v69, v48, v69
	v_exp_f32_e32 v79, v69
	v_add_f32_e32 v57, v63, v77
	v_pk_add_f32 v[86:87], v[86:87], 1.0 op_sel_hi:[1,0] neg_lo:[1,0] neg_hi:[1,0]
	v_sub_f32_e32 v68, v48, v68
	v_sub_f32_e32 v57, v48, v57
	v_exp_f32_e32 v70, v68
	v_pk_mul_f32 v[68:69], v[86:87], v[78:79]
	v_exp_f32_e32 v78, v57
	v_add_f32_e32 v57, v62, v77
	v_sub_f32_e32 v57, v48, v57
	v_exp_f32_e32 v79, v57
	v_add_f32_e32 v57, v59, v77
	v_add_f32_e32 v67, v67, v77
	v_sub_f32_e32 v57, v48, v57
	v_exp_f32_e32 v94, v94
	v_exp_f32_e32 v95, v95
	v_exp_f32_e32 v92, v92
	v_exp_f32_e32 v93, v93
	v_sub_f32_e32 v67, v48, v67
	v_exp_f32_e32 v62, v57
	v_add_f32_e32 v57, v58, v77
	v_exp_f32_e32 v74, v71
	v_exp_f32_e32 v71, v67
	v_sub_f32_e32 v57, v48, v57
	v_exp_f32_e32 v63, v57
	v_pk_add_f32 v[94:95], v[94:95], 1.0 op_sel_hi:[1,0] neg_lo:[1,0] neg_hi:[1,0]
	v_pk_add_f32 v[92:93], v[92:93], 1.0 op_sel_hi:[1,0] neg_lo:[1,0] neg_hi:[1,0]
	v_add_f32_e32 v56, v56, v77
	v_add_f32_e32 v55, v55, v77
	v_add_f32_e32 v54, v54, v77
	v_add_f32_e32 v53, v53, v77
	v_add_f32_e32 v52, v52, v77
	v_add_f32_e32 v51, v51, v77
	v_pk_mul_f32 v[70:71], v[94:95], v[70:71]
	v_pk_mul_f32 v[58:59], v[92:93], v[78:79]
	v_sub_f32_e32 v56, v48, v56
	v_sub_f32_e32 v55, v48, v55
	v_sub_f32_e32 v54, v48, v54
	v_sub_f32_e32 v53, v48, v53
	v_sub_f32_e32 v52, v48, v52
	v_sub_f32_e32 v51, v48, v51
	v_cvt_pk_bf16_f32 v68, v68, v69
	v_cvt_pk_bf16_f32 v69, v70, v71
	v_cvt_pk_bf16_f32 v70, v58, v59
	v_pk_mul_f32 v[58:59], v[72:73], v[62:63]
	v_exp_f32_e32 v56, v56
	v_exp_f32_e32 v57, v55
	v_exp_f32_e32 v62, v54
	v_exp_f32_e32 v63, v53
	v_exp_f32_e32 v52, v52
	v_exp_f32_e32 v53, v51
	v_add_f32_e32 v50, v50, v77
	v_sub_f32_e32 v50, v48, v50
	v_sub_f32_e32 v49, v48, v49
	v_exp_f32_e32 v50, v50
	v_exp_f32_e32 v51, v49
	v_pk_add_f32 v[74:75], v[74:75], 1.0 op_sel_hi:[1,0] neg_lo:[1,0] neg_hi:[1,0]
	v_pk_mul_f32 v[54:55], v[82:83], v[56:57]
	v_pk_mul_f32 v[56:57], v[98:99], v[62:63]
	v_pk_mul_f32 v[52:53], v[74:75], v[52:53]
	v_cvt_pk_bf16_f32 v54, v54, v55
	v_cvt_pk_bf16_f32 v55, v56, v57
	v_cvt_pk_bf16_f32 v56, v52, v53
	v_pk_add_f32 v[52:53], v[102:103], 1.0 op_sel_hi:[1,0] neg_lo:[1,0] neg_hi:[1,0]
	v_cvt_pk_bf16_f32 v71, v58, v59
	v_pk_mul_f32 v[50:51], v[52:53], v[50:51]
	s_nop 0
	v_cvt_pk_bf16_f32 v57, v50, v51
	ds_write_b128 v88, v[68:71] offset:16384
	ds_write_b128 v89, v[54:57] offset:16384
	s_and_saveexec_b64 s[6:7], s[4:5]
	v_exp_f32_e32 v48, v48
	ds_write_b32 v90, v48 offset:33280
	s_or_b64 exec, exec, s[6:7]
	v_mov_b32_e32 v48, v145
	v_cvt_pk_fp8_f32 v48, v32, v33
	v_mov_b32_e32 v32, v145
	v_cvt_pk_fp8_f32 v32, v36, v37
	v_mov_b32_e32 v33, v145
	v_mov_b32_e32 v36, v145
	v_cvt_pk_fp8_f32 v48, v34, v35 op_sel:[0,0,1]
	v_mov_b32_e32 v34, v145
	v_cvt_pk_fp8_f32 v33, v40, v41
	v_cvt_pk_fp8_f32 v36, v44, v45
	v_cvt_pk_fp8_f32 v34, v16, v17
	v_mov_b32_e32 v16, v145
	v_cvt_pk_fp8_f32 v16, v20, v21
	v_mov_b32_e32 v17, v145
	v_mov_b32_e32 v20, v145
	v_cvt_pk_fp8_f32 v17, v24, v25
	v_cvt_pk_fp8_f32 v20, v28, v29
	v_cvt_pk_fp8_f32 v32, v38, v39 op_sel:[0,0,1]
	v_cvt_pk_fp8_f32 v33, v42, v43 op_sel:[0,0,1]
	v_cvt_pk_fp8_f32 v36, v46, v47 op_sel:[0,0,1]
	v_cvt_pk_fp8_f32 v34, v18, v19 op_sel:[0,0,1]
	v_cvt_pk_fp8_f32 v16, v22, v23 op_sel:[0,0,1]
	v_cvt_pk_fp8_f32 v17, v26, v27 op_sel:[0,0,1]
	v_cvt_pk_fp8_f32 v20, v30, v31 op_sel:[0,0,1]
	ds_write2_b32 v64, v48, v32 offset1:2
	ds_write2_b32 v65, v33, v36 offset1:2
	ds_write2_b32 v104, v34, v16 offset1:2
	ds_write2_b32 v101, v17, v20 offset1:2
	s_waitcnt lgkmcnt(0)
	s_barrier
	ds_read_b128 v[16:19], v60 offset:40960
	ds_read_b128 v[20:23], v61 offset:40960
	s_add_i32 s34, s97, s56
	s_lshl_b64 s[4:5], s[34:35], 14
	v_lshl_add_u64 v[24:25], v[80:81], 0, s[4:5]
	v_lshl_add_u64 v[24:25], v[24:25], 0, v[144:145]
	s_waitcnt lgkmcnt(1)
	global_store_dwordx4 v[24:25], v[16:19], off
	s_waitcnt lgkmcnt(0)
	global_store_dwordx4 v[24:25], v[20:23], off offset:16
	s_and_saveexec_b64 s[4:5], s[18:19]
	v_mov_b32_e32 v16, s89
	ds_write_b32 v16, v66
	s_or_b64 exec, exec, s[4:5]
	s_waitcnt vmcnt(0) lgkmcnt(0)
	s_barrier
	s_andn2_b64 vcc, exec, s[44:45]
	s_cbranch_vccnz .LBB0_643
	v_mov_b32_e32 v16, v244
	s_nop 0
	v_cmp_eq_u32_e32 vcc, 0, v16
	s_and_saveexec_b64 s[4:5], vcc
	s_cbranch_execz .LBB0_696
	s_mov_b64 s[6:7], s[0:1]
	v_readlane_b32 s98, v252, 3
	v_readlane_b32 s99, v252, 4
	s_nop 1
	s_cmp_eq_u64 s[98:99], 0
	s_cbranch_scc1 .Lchain_nowb
	buffer_wbl2 sc1
.Lchain_nowb:
	s_waitcnt vmcnt(0) lgkmcnt(0)
	s_waitcnt vmcnt(0)
	s_load_dwordx2 s[6:7], s[6:7], 0xa8
	s_lshl_b32 s8, s96, 6
	s_ashr_i32 s9, s8, 31
	s_lshl_b64 s[8:9], s[8:9], 2
	s_waitcnt lgkmcnt(0)
	s_add_u32 s6, s6, s8
	s_addc_u32 s7, s7, s9
	global_store_dword v151, v147, s[6:7] sc1
